# FFN down K loop rotated across the slice barrier: last 4 MFMAs behind the next slice's first fragment reads, LDS writes finished in the first half, addresses formed before the barrier
# speedup vs baseline: 1.0547x; 1.0019x over previous
; DI int ltid() { int t = threadIdx.x; asm volatile("" : "+v"(t)); return t; }
; template <int BM, class Epi>
; DI void gemm_tile(const bf16_t* __restrict__ A, int lda, const bf16_t* __restrict__ B, int ldb, int K, int row0, int col0, const Epi& epi, char* smem) {
;     ...
;     const int tid = ltid(), lane = tid & 63, wave = tid >> 6, wm = wave >> 2, wn = wave & 3;
;     const int l31 = lane & 31, hh = lane >> 5, q = (lane & 15) >> 2, p = lane & 3, nblk = (lane >> 4) & 1;
;     f32x16 acc[MI][2];
; #pragma unroll
;     for (int i = 0; i < MI; ++i)
; #pragma unroll
;         for (int j = 0; j < 2; ++j)
; #pragma unroll
;             for (int r = 0; r < 16; ++r) acc[i][j][r] = 0.f;
;     u32x4 ra[NA_], rb[4];
;     const bf16_t* ag = A + (size_t)(row0 + (tid >> 3)) * lda + (tid & 7) * 8;
;     const bf16_t* bg = B + (size_t)(tid >> 5) * ldb + col0 + (tid & 31) * 8;
;     const int aw = (tid >> 3) * GA_S + (tid & 7) * 16, bw = BM * GA_S + (tid >> 5) * GB_S + (tid & 31) * 16;
;     const int nk = K >> 6;
;     const int xoff = (wm * (BM / 2) + l31) * GA_S + hh * 16;
;     const int woff = BM * GA_S + (hh * 8 + q) * GB_S + (wn * 64 + nblk * 16 + 4 * p) * 2;
; #pragma unroll
;     for (int i = 0; i < NA_; ++i) ra[i] = *(const u32x4*)(ag + (size_t)(64 * i) * lda);
; #pragma unroll
;     for (int i = 0; i < 4; ++i) rb[i] = *(const u32x4*)(bg + (size_t)(16 * i) * ldb);
;     __syncthreads();
; #pragma unroll
;     for (int i = 0; i < NA_; ++i) *(u32x4*)(smem + aw + 64 * i * GA_S) = ra[i];
; #pragma unroll
;     for (int i = 0; i < 4; ++i) *(u32x4*)(smem + bw + 16 * i * GB_S) = rb[i];
;     if (nk > 1) {
; #pragma unroll
;         for (int i = 0; i < NA_; ++i) ra[i] = *(const u32x4*)(ag + 64 + (size_t)(64 * i) * lda);
; #pragma unroll
;         for (int i = 0; i < 4; ++i) rb[i] = *(const u32x4*)(bg + (size_t)(64 + 16 * i) * ldb);
;     }
;     __syncthreads();
.LBB0_1486:
	s_lshr_b32 s0, s16, 2
	s_add_i32 s0, s0, s10
	s_lshl_b32 s10, s16, 3
	s_lshl_b32 s1, s11, 5
	s_and_b32 s10, s10, 24
	s_or_b32 s1, s1, s10
	s_or_b32 s1, s1, s14
	v_mov_b32_e32 v175, v194
	s_lshl_b32 s16, s1, 8
	s_lshl_b32 s10, s0, 8
	v_ashrrev_i32_e32 v46, 3, v175
	v_add_u32_e32 v47, s16, v46
	v_mov_b64_e32 v[0:1], s[34:35]
	s_movk_i32 s17, 0x1600
	v_lshlrev_b32_e32 v2, 4, v175
	v_mad_i64_i32 v[0:1], s[0:1], v47, s17, v[0:1]
	v_and_b32_e32 v172, 0x70, v2
	s_ashr_i32 s11, s10, 31
	v_lshl_add_u64 v[32:33], v[0:1], 0, v[172:173]
	s_lshl_b64 s[0:1], s[10:11], 1
	s_mov_b32 s11, 0x58000
	v_ashrrev_i32_e32 v34, 5, v175
	v_add_co_u32_e32 v40, vcc, s11, v32
	v_ashrrev_i32_e32 v35, 31, v34
	s_nop 0
	v_addc_co_u32_e32 v41, vcc, 0, v33, vcc
	s_mov_b32 s11, 0xb0000
	v_lshlrev_b64 v[36:37], 11, v[34:35]
	v_add_co_u32_e32 v42, vcc, s11, v32
	v_and_b32_e32 v176, 31, v175
	v_lshl_add_u64 v[0:1], v[160:161], 0, v[36:37]
	v_addc_co_u32_e32 v43, vcc, 0, v33, vcc
	s_mov_b32 s11, 0x108000
	v_lshl_add_u64 v[0:1], v[0:1], 0, s[0:1]
	v_lshlrev_b32_e32 v164, 4, v176
	v_mov_b32_e32 v165, v173
	v_add_co_u32_e32 v44, vcc, s11, v32
	v_lshl_add_u64 v[38:39], v[0:1], 0, v[164:165]
	s_nop 0
	v_addc_co_u32_e32 v45, vcc, 0, v33, vcc
	s_mov_b32 s11, 0x8000
	v_add_co_u32_e32 v20, vcc, s11, v38
	s_mov_b32 s11, 0x10000
	s_nop 0
	v_addc_co_u32_e32 v21, vcc, 0, v39, vcc
	v_add_co_u32_e32 v24, vcc, s11, v38
	s_mov_b32 s11, 0x18000
	s_nop 0
	v_addc_co_u32_e32 v25, vcc, 0, v39, vcc
	s_waitcnt vmcnt(1)
	v_add_co_u32_e32 v28, vcc, s11, v38
	global_load_dwordx4 v[0:3], v[40:41], off
	global_load_dwordx4 v[4:7], v[42:43], off
	v_addc_co_u32_e32 v29, vcc, 0, v39, vcc
	global_load_dwordx4 v[8:11], v[32:33], off
	global_load_dwordx4 v[12:15], v[38:39], off
	global_load_dwordx4 v[16:19], v[44:45], off
	s_nop 0
	global_load_dwordx4 v[20:23], v[20:21], off
	s_nop 0
	global_load_dwordx4 v[24:27], v[24:25], off
	s_nop 0
	global_load_dwordx4 v[28:31], v[28:29], off
	v_bfe_u32 v177, v175, 5, 1
	v_bfe_u32 v35, v175, 2, 2
	v_mul_lo_u32 v182, v34, s84
	v_lshl_or_b32 v34, v177, 3, v35
	v_mad_u64_u32 v[166:167], s[18:19], v46, s85, v[172:173]
	v_mul_u32_u24_e32 v180, 0x240, v34
	v_add_u32_e32 v183, v182, v164
	v_add_u32_e32 v34, 0, v166
	v_add_u32_e32 v46, 0, v183
	s_waitcnt vmcnt(63) expcnt(7) lgkmcnt(15)
	s_barrier
	v_mad_i64_i32 v[168:169], s[18:19], v47, s17, 0
	s_mov_b32 s17, 0x28000
	v_ashrrev_i32_e32 v48, 1, v175
	v_and_b32_e32 v49, 0xd0, v175
	v_lshlrev_b32_e32 v50, 2, v175
	v_and_b32_e32 v178, 0xffffff80, v48
	v_and_or_b32 v35, v50, 12, v49
	v_or_b32_e32 v48, v178, v176
	s_mov_b32 s11, 0
	v_lshlrev_b32_e32 v179, 4, v177
	v_mul_lo_u32 v167, v48, s85
	v_lshlrev_b32_e32 v181, 1, v35
	v_or_b32_e32 v168, v168, v172
	s_mov_b32 s18, 0x2c40000
	s_mov_b32 s19, 0x115db000
	s_mov_b32 s20, 0x2c48000
	s_mov_b32 s21, 0x11633000
	s_mov_b32 s22, 0x2c50000
	s_mov_b32 s23, 0x1168b000
	s_mov_b32 s24, 0x2c58000
	s_mov_b64 s[26:27], 0x80
	s_mov_b64 s[28:29], 0x20000
	s_waitcnt vmcnt(5)
	ds_write_b128 v34, v[8:11]
	ds_write_b128 v34, v[0:3] offset:9216
	ds_write_b128 v34, v[4:7] offset:18432
	s_waitcnt vmcnt(3)
	ds_write_b128 v34, v[16:19] offset:27648
	ds_write_b128 v46, v[12:15] offset:36864
	s_waitcnt vmcnt(2)
	ds_write_b128 v46, v[20:23] offset:46080
	s_waitcnt vmcnt(1)
	ds_write_b128 v46, v[24:27] offset:55296
	s_waitcnt vmcnt(0)
	ds_write_b128 v46, v[28:31] offset:64512
	v_add_co_u32_e32 v0, vcc, s86, v38
	global_load_dwordx4 v[152:155], v[32:33], off offset:128
	global_load_dwordx4 v[144:147], v[40:41], off offset:128
	global_load_dwordx4 v[136:139], v[42:43], off offset:128
	global_load_dwordx4 v[128:131], v[44:45], off offset:128
	v_addc_co_u32_e32 v1, vcc, 0, v39, vcc
	v_add_co_u32_e32 v2, vcc, s17, v38
	s_mov_b32 s17, 0x30000
	s_nop 0
	v_addc_co_u32_e32 v3, vcc, 0, v39, vcc
	global_load_dwordx4 v[156:159], v[0:1], off
	global_load_dwordx4 v[148:151], v[2:3], off
	v_add_co_u32_e32 v0, vcc, s17, v38
	s_mov_b32 s17, 0x38000
	s_nop 0
	v_addc_co_u32_e32 v1, vcc, 0, v39, vcc
	v_add_co_u32_e32 v2, vcc, s17, v38
	s_mov_b32 s17, 0x11583000
	s_nop 0
	v_addc_co_u32_e32 v3, vcc, 0, v39, vcc
	global_load_dwordx4 v[140:143], v[0:1], off
	global_load_dwordx4 v[132:135], v[2:3], off
	v_lshl_add_u64 v[0:1], v[162:163], 0, v[36:37]
	v_lshl_add_u64 v[0:1], v[0:1], 0, v[164:165]
	v_lshl_add_u64 v[170:171], v[0:1], 0, s[0:1]
	v_mov_b32_e32 v0, 0
	v_mov_b32_e32 v1, v0
	v_mov_b32_e32 v2, v0
	v_mov_b32_e32 v3, v0
	v_mov_b32_e32 v4, v0
	v_mov_b32_e32 v5, v0
	v_mov_b32_e32 v6, v0
	v_mov_b32_e32 v7, v0
	v_mov_b32_e32 v8, v0
	v_mov_b32_e32 v9, v0
	v_mov_b32_e32 v10, v0
	v_mov_b32_e32 v11, v0
	v_mov_b32_e32 v12, v0
	v_mov_b32_e32 v13, v0
	v_mov_b32_e32 v14, v0
	v_mov_b32_e32 v15, v0
	v_mov_b32_e32 v16, v0
	v_mov_b32_e32 v17, v0
	v_mov_b32_e32 v18, v0
	v_mov_b32_e32 v19, v0
	v_mov_b32_e32 v20, v0
	v_mov_b32_e32 v21, v0
	v_mov_b32_e32 v22, v0
	v_mov_b32_e32 v23, v0
	v_mov_b32_e32 v24, v0
	v_mov_b32_e32 v25, v0
	v_mov_b32_e32 v26, v0
	v_mov_b32_e32 v27, v0
	v_mov_b32_e32 v28, v0
	v_mov_b32_e32 v29, v0
	v_mov_b32_e32 v30, v0
	v_mov_b32_e32 v31, v0
	v_mov_b32_e32 v32, v0
	v_mov_b32_e32 v33, v0
	v_mov_b32_e32 v34, v0
	v_mov_b32_e32 v35, v0
	v_mov_b32_e32 v36, v0
	v_mov_b32_e32 v37, v0
	v_mov_b32_e32 v38, v0
	v_mov_b32_e32 v39, v0
	v_mov_b32_e32 v40, v0
	v_mov_b32_e32 v41, v0
	v_mov_b32_e32 v42, v0
	v_mov_b32_e32 v43, v0
	v_mov_b32_e32 v44, v0
	v_mov_b32_e32 v45, v0
	v_mov_b32_e32 v46, v0
	v_mov_b32_e32 v47, v0
	v_mov_b32_e32 v48, v0
	v_mov_b32_e32 v49, v0
	v_mov_b32_e32 v50, v0
	v_mov_b32_e32 v51, v0
	v_mov_b32_e32 v52, v0
	v_mov_b32_e32 v53, v0
	v_mov_b32_e32 v54, v0
	v_mov_b32_e32 v55, v0
	v_mov_b32_e32 v56, v0
; DI f32x16 mfma32(bf16x8 a, bf16x8 b, f32x16 c) { return __builtin_amdgcn_mfma_f32_32x32x16_bf16(a, b, c, 0, 0, 0); }
; DI s16x4 tr_read(const char* p) { bfx4 r = __builtin_amdgcn_ds_read_tr16_b64_v4bf16((LDS_AS bfx4*)p); return __builtin_bit_cast(s16x4, r); }
; DI bf16x8 cat8(s16x4 lo, s16x4 hi) { return __builtin_shufflevector(lo, hi, 0, 1, 2, 3, 4, 5, 6, 7); }
; template <int BM, class Epi>
; DI void gemm_tile(const bf16_t* __restrict__ A, int lda, const bf16_t* __restrict__ B, int ldb, int K, int row0, int col0, const Epi& epi, char* smem) {
;     ...
; #pragma unroll
;     for (int i = 0; i < MI; ++i)
; #pragma unroll
;         for (int j = 0; j < 2; ++j)
; #pragma unroll
;             for (int r = 0; r < 16; ++r) acc[i][j][r] = 0.f;
;     ...
;     for (int kt = 0; kt < nk; ++kt) {
;         const char* cur = smem + (kt & 1) * GSTAGE;
;         char* nxt = smem + ((kt & 1) ^ 1) * GSTAGE;
;         const bool w1 = kt + 1 < nk, l2 = kt + 2 < nk;
;         const bf16_t* a2 = ag + (size_t)(kt + 2) * 64; const bf16_t* b2 = bg + (size_t)(kt + 2) * 64 * ldb;
; #pragma unroll
;         for (int s = 0; s < 4; ++s) {
;             bf16x8 xf[MI], wf[2];
; #pragma unroll
;             for (int mi = 0; mi < MI; ++mi) xf[mi] = *(const bf16x8*)(cur + xoff + mi * 32 * GA_S + s * 32);
; #pragma unroll
;             for (int ni = 0; ni < 2; ++ni) {
;                 const char* wp = cur + woff + s * 16 * GB_S + ni * 64;
;                 wf[ni] = cat8(tr_read(wp), tr_read(wp + 4 * GB_S));
;             }
; #pragma unroll
;             for (int mi = 0; mi < MI; ++mi)
; #pragma unroll
;                 for (int ni = 0; ni < 2; ++ni) acc[mi][ni] = mfma32(wf[ni], xf[mi], acc[mi][ni]);
;             if (w1) {
;                 if (s < NA_) *(u32x4*)(nxt + aw + 64 * s * GA_S) = ra[s];
;                 *(u32x4*)(nxt + bw + 16 * s * GB_S) = rb[s];
;             }
;             if (l2) {
;                 if (s < NA_) ra[s] = *(const u32x4*)(a2 + (size_t)(64 * s) * lda);
;                 rb[s] = *(const u32x4*)(b2 + (size_t)(16 * s) * ldb);
;             }
;         }
	v_mov_b32_e32 v57, v0
	v_mov_b32_e32 v58, v0
	v_mov_b32_e32 v59, v0
	v_mov_b32_e32 v60, v0
	v_mov_b32_e32 v61, v0
	v_mov_b32_e32 v62, v0
	v_mov_b32_e32 v63, v0
	v_mov_b32_e32 v64, v0
	v_mov_b32_e32 v65, v0
	v_mov_b32_e32 v66, v0
	v_mov_b32_e32 v67, v0
	v_mov_b32_e32 v68, v0
	v_mov_b32_e32 v69, v0
	v_mov_b32_e32 v70, v0
	v_mov_b32_e32 v71, v0
	v_mov_b32_e32 v72, v0
	v_mov_b32_e32 v73, v0
	v_mov_b32_e32 v74, v0
	v_mov_b32_e32 v75, v0
	v_mov_b32_e32 v76, v0
	v_mov_b32_e32 v77, v0
	v_mov_b32_e32 v78, v0
	v_mov_b32_e32 v79, v0
	v_mov_b32_e32 v80, v0
	v_mov_b32_e32 v81, v0
	v_mov_b32_e32 v82, v0
	v_mov_b32_e32 v83, v0
	v_mov_b32_e32 v84, v0
	v_mov_b32_e32 v85, v0
	v_mov_b32_e32 v86, v0
	v_mov_b32_e32 v87, v0
	v_mov_b32_e32 v88, v0
	v_mov_b32_e32 v89, v0
	v_mov_b32_e32 v90, v0
	v_mov_b32_e32 v91, v0
	v_mov_b32_e32 v92, v0
	v_mov_b32_e32 v93, v0
	v_mov_b32_e32 v94, v0
	v_mov_b32_e32 v95, v0
	v_mov_b32_e32 v96, v0
	v_mov_b32_e32 v97, v0
	v_mov_b32_e32 v98, v0
	v_mov_b32_e32 v99, v0
	v_mov_b32_e32 v100, v0
	v_mov_b32_e32 v101, v0
	v_mov_b32_e32 v102, v0
	v_mov_b32_e32 v103, v0
	v_mov_b32_e32 v104, v0
	v_mov_b32_e32 v105, v0
	v_mov_b32_e32 v106, v0
	v_mov_b32_e32 v107, v0
	v_mov_b32_e32 v108, v0
	v_mov_b32_e32 v109, v0
	v_mov_b32_e32 v110, v0
	v_mov_b32_e32 v111, v0
	v_mov_b32_e32 v112, v0
	v_mov_b32_e32 v113, v0
	v_mov_b32_e32 v114, v0
	v_mov_b32_e32 v115, v0
	v_mov_b32_e32 v116, v0
	v_mov_b32_e32 v117, v0
	v_mov_b32_e32 v118, v0
	v_mov_b32_e32 v119, v0
	v_mov_b32_e32 v120, v0
	v_mov_b32_e32 v121, v0
	v_mov_b32_e32 v122, v0
	v_mov_b32_e32 v123, v0
	v_mov_b32_e32 v124, v0
	v_mov_b32_e32 v125, v0
	v_mov_b32_e32 v126, v0
	v_mov_b32_e32 v127, v0
	s_waitcnt lgkmcnt(0)
	s_barrier
	s_waitcnt vmcnt(0)
	s_and_b32 s0, s11, 1
	s_mul_i32 s1, s0, 0x12000
	v_add3_u32 v172, s1, v180, v181
	v_add3_u32 v165, s1, v167, v179
	s_xor_b32 s0, s0, 1
	s_mul_i32 s0, s0, 0x12000
	v_add_u32_e32 v233, 0x9000, v172
	v_add_u32_e32 v217, s0, v166
	v_add_u32_e32 v232, s0, v183
	ds_read_b64_tr_b16 v[234:235], v172 offset:36864
	ds_read_b64_tr_b16 v[236:237], v172 offset:39168
	ds_read_b128 v[184:187], v165
	ds_read_b64_tr_b16 v[238:239], v172 offset:36928
	ds_read_b64_tr_b16 v[240:241], v172 offset:39232
	ds_read_b128 v[188:191], v165 offset:4608
	s_branch .Lmy_g_mid
.LBB0_1487:
	ds_read_b64_tr_b16 v[234:235], v172 offset:36864
	ds_read_b64_tr_b16 v[236:237], v172 offset:39168
	ds_read_b128 v[184:187], v165
	ds_read_b64_tr_b16 v[238:239], v172 offset:36928
	ds_read_b64_tr_b16 v[240:241], v172 offset:39232
	ds_read_b128 v[188:191], v165 offset:4608
	v_mfma_f32_32x32x16_bf16 v[48:63], v[242:245], v[218:221], v[48:63]
	v_mfma_f32_32x32x16_bf16 v[32:47], v[246:249], v[218:221], v[32:47]
	v_mfma_f32_32x32x16_bf16 v[16:31], v[242:245], v[222:225], v[16:31]
	v_mfma_f32_32x32x16_bf16 v[0:15], v[246:249], v[222:225], v[0:15]
.Lmy_g_mid:
	ds_read_b128 v[218:221], v165 offset:9216
	ds_read_b128 v[222:225], v165 offset:13824
	v_add_u32_e32 v192, s17, v168
	v_add_u32_e32 v193, s18, v170
	v_add_u32_e32 v226, s19, v168
	v_add_u32_e32 v227, s20, v170
	v_add_u32_e32 v228, s21, v168
	v_add_u32_e32 v229, s22, v170
	v_add_u32_e32 v230, s23, v168
	v_add_u32_e32 v231, s24, v170
	v_lshl_add_u64 v[170:171], v[170:171], 0, s[28:29]
	v_lshl_add_u64 v[168:169], v[168:169], 0, s[26:27]
	s_add_i32 s11, s11, 1
	s_waitcnt lgkmcnt(5)
	v_mfma_f32_32x32x16_bf16 v[112:127], v[234:237], v[184:187], v[112:127]
	ds_read_b64_tr_b16 v[242:243], v172 offset:46080
	ds_read_b64_tr_b16 v[244:245], v172 offset:48384
	ds_read_b64_tr_b16 v[246:247], v172 offset:46144
	ds_read_b64_tr_b16 v[248:249], v172 offset:48448
	s_waitcnt lgkmcnt(7)
	v_mfma_f32_32x32x16_bf16 v[96:111], v[238:241], v[184:187], v[96:111]
	ds_read_b128 v[184:187], v165 offset:32
	s_waitcnt lgkmcnt(7)
	v_mfma_f32_32x32x16_bf16 v[80:95], v[234:237], v[188:191], v[80:95]
	v_mfma_f32_32x32x16_bf16 v[64:79], v[238:241], v[188:191], v[64:79]
	ds_read_b128 v[188:191], v165 offset:4640
	s_waitcnt vmcnt(7)
	ds_write_b128 v217, v[152:155]
	s_waitcnt vmcnt(6)
	ds_write_b128 v232, v[156:159] offset:36864
	global_load_dwordx4 v[152:155], v192, s[94:95] offset:768
	global_load_dwordx4 v[156:159], v193, s[94:95]
	s_waitcnt lgkmcnt(9)
	v_mfma_f32_32x32x16_bf16 v[48:63], v[234:237], v[218:221], v[48:63]
	v_mfma_f32_32x32x16_bf16 v[32:47], v[238:241], v[218:221], v[32:47]
	ds_read_b128 v[218:221], v165 offset:9248
	s_waitcnt lgkmcnt(9)
	v_mfma_f32_32x32x16_bf16 v[16:31], v[234:237], v[222:225], v[16:31]
	v_mfma_f32_32x32x16_bf16 v[0:15], v[238:241], v[222:225], v[0:15]
	ds_read_b128 v[222:225], v165 offset:13856
	s_waitcnt vmcnt(7)
	ds_write_b128 v217, v[144:147] offset:9216
	s_waitcnt vmcnt(6)
	ds_write_b128 v232, v[148:151] offset:46080
	global_load_dwordx4 v[144:147], v226, s[94:95] offset:768
	global_load_dwordx4 v[148:151], v227, s[94:95]
	s_waitcnt lgkmcnt(7)
	v_mfma_f32_32x32x16_bf16 v[112:127], v[242:245], v[184:187], v[112:127]
	ds_read_b64_tr_b16 v[234:235], v172 offset:55296
	ds_read_b64_tr_b16 v[236:237], v172 offset:57600
	ds_read_b64_tr_b16 v[238:239], v172 offset:55360
	ds_read_b64_tr_b16 v[240:241], v172 offset:57664
	v_mfma_f32_32x32x16_bf16 v[96:111], v[246:249], v[184:187], v[96:111]
	ds_read_b128 v[184:187], v165 offset:64
	s_waitcnt lgkmcnt(11)
	v_mfma_f32_32x32x16_bf16 v[80:95], v[242:245], v[188:191], v[80:95]
	v_mfma_f32_32x32x16_bf16 v[64:79], v[246:249], v[188:191], v[64:79]
	ds_read_b128 v[188:191], v165 offset:4672
	s_waitcnt vmcnt(7)
	ds_write_b128 v217, v[136:139] offset:18432
	s_waitcnt vmcnt(6)
	ds_write_b128 v232, v[140:143] offset:55296
	global_load_dwordx4 v[136:139], v228, s[94:95] offset:768
	global_load_dwordx4 v[140:143], v229, s[94:95]
	s_waitcnt lgkmcnt(11)
; DI f32x16 mfma32(bf16x8 a, bf16x8 b, f32x16 c) { return __builtin_amdgcn_mfma_f32_32x32x16_bf16(a, b, c, 0, 0, 0); }
; DI s16x4 tr_read(const char* p) { bfx4 r = __builtin_amdgcn_ds_read_tr16_b64_v4bf16((LDS_AS bfx4*)p); return __builtin_bit_cast(s16x4, r); }
; DI bf16x8 cat8(s16x4 lo, s16x4 hi) { return __builtin_shufflevector(lo, hi, 0, 1, 2, 3, 4, 5, 6, 7); }
; template <int BM, class Epi>
; DI void gemm_tile(const bf16_t* __restrict__ A, int lda, const bf16_t* __restrict__ B, int ldb, int K, int row0, int col0, const Epi& epi, char* smem) {
;     ...
;     for (int kt = 0; kt < nk; ++kt) {
;         const char* cur = smem + (kt & 1) * GSTAGE;
;         char* nxt = smem + ((kt & 1) ^ 1) * GSTAGE;
;         const bool w1 = kt + 1 < nk, l2 = kt + 2 < nk;
;         const bf16_t* a2 = ag + (size_t)(kt + 2) * 64; const bf16_t* b2 = bg + (size_t)(kt + 2) * 64 * ldb;
; #pragma unroll
;         for (int s = 0; s < 4; ++s) {
;             bf16x8 xf[MI], wf[2];
; #pragma unroll
;             for (int mi = 0; mi < MI; ++mi) xf[mi] = *(const bf16x8*)(cur + xoff + mi * 32 * GA_S + s * 32);
; #pragma unroll
;             for (int ni = 0; ni < 2; ++ni) {
;                 const char* wp = cur + woff + s * 16 * GB_S + ni * 64;
;                 wf[ni] = cat8(tr_read(wp), tr_read(wp + 4 * GB_S));
;             }
; #pragma unroll
;             for (int mi = 0; mi < MI; ++mi)
; #pragma unroll
;                 for (int ni = 0; ni < 2; ++ni) acc[mi][ni] = mfma32(wf[ni], xf[mi], acc[mi][ni]);
;             if (w1) {
;                 if (s < NA_) *(u32x4*)(nxt + aw + 64 * s * GA_S) = ra[s];
;                 *(u32x4*)(nxt + bw + 16 * s * GB_S) = rb[s];
;             }
;             if (l2) {
;                 if (s < NA_) ra[s] = *(const u32x4*)(a2 + (size_t)(64 * s) * lda);
;                 rb[s] = *(const u32x4*)(b2 + (size_t)(16 * s) * ldb);
;             }
;         }
	v_mfma_f32_32x32x16_bf16 v[48:63], v[242:245], v[218:221], v[48:63]
	v_mfma_f32_32x32x16_bf16 v[32:47], v[246:249], v[218:221], v[32:47]
	ds_read_b128 v[218:221], v165 offset:9280
	s_waitcnt lgkmcnt(11)
	v_mfma_f32_32x32x16_bf16 v[16:31], v[242:245], v[222:225], v[16:31]
	v_mfma_f32_32x32x16_bf16 v[0:15], v[246:249], v[222:225], v[0:15]
	ds_read_b128 v[222:225], v165 offset:13888
	s_waitcnt vmcnt(7)
	ds_write_b128 v217, v[128:131] offset:27648
	s_waitcnt vmcnt(6)
	ds_write_b128 v232, v[132:135] offset:64512
	global_load_dwordx4 v[128:131], v230, s[94:95] offset:768
	global_load_dwordx4 v[132:135], v231, s[94:95]
	s_waitcnt lgkmcnt(7)
	v_mfma_f32_32x32x16_bf16 v[112:127], v[234:237], v[184:187], v[112:127]
	ds_read_b64_tr_b16 v[242:243], v172 offset:64512
	ds_read_b64_tr_b16 v[244:245], v233 offset:29952
	ds_read_b64_tr_b16 v[246:247], v172 offset:64576
	ds_read_b64_tr_b16 v[248:249], v233 offset:30016
	v_mfma_f32_32x32x16_bf16 v[96:111], v[238:241], v[184:187], v[96:111]
	ds_read_b128 v[184:187], v165 offset:96
	s_waitcnt lgkmcnt(11)
	v_mfma_f32_32x32x16_bf16 v[80:95], v[234:237], v[188:191], v[80:95]
	v_mfma_f32_32x32x16_bf16 v[64:79], v[238:241], v[188:191], v[64:79]
	ds_read_b128 v[188:191], v165 offset:4704
	s_waitcnt lgkmcnt(9)
	v_mfma_f32_32x32x16_bf16 v[48:63], v[234:237], v[218:221], v[48:63]
	v_mfma_f32_32x32x16_bf16 v[32:47], v[238:241], v[218:221], v[32:47]
	ds_read_b128 v[218:221], v165 offset:9312
	s_waitcnt lgkmcnt(9)
	v_mfma_f32_32x32x16_bf16 v[16:31], v[234:237], v[222:225], v[16:31]
	v_mfma_f32_32x32x16_bf16 v[0:15], v[238:241], v[222:225], v[0:15]
	ds_read_b128 v[222:225], v165 offset:13920
	s_waitcnt lgkmcnt(3)
	v_mfma_f32_32x32x16_bf16 v[112:127], v[242:245], v[184:187], v[112:127]
	v_mfma_f32_32x32x16_bf16 v[96:111], v[246:249], v[184:187], v[96:111]
	s_waitcnt lgkmcnt(2)
	v_mfma_f32_32x32x16_bf16 v[80:95], v[242:245], v[188:191], v[80:95]
	v_mfma_f32_32x32x16_bf16 v[64:79], v[246:249], v[188:191], v[64:79]
	s_and_b32 s0, s11, 1
	s_mul_i32 s1, s0, 0x12000
	v_add3_u32 v172, s1, v180, v181
	v_add3_u32 v165, s1, v167, v179
	s_xor_b32 s0, s0, 1
	s_mul_i32 s0, s0, 0x12000
	v_add_u32_e32 v233, 0x9000, v172
	v_add_u32_e32 v217, s0, v166
	v_add_u32_e32 v232, s0, v183
	s_cmp_eq_u32 s11, 42
	s_waitcnt lgkmcnt(0)
	s_barrier
	s_cbranch_scc0 .LBB0_1487
	v_mfma_f32_32x32x16_bf16 v[48:63], v[242:245], v[218:221], v[48:63]
	v_mfma_f32_32x32x16_bf16 v[32:47], v[246:249], v[218:221], v[32:47]
	v_mfma_f32_32x32x16_bf16 v[16:31], v[242:245], v[222:225], v[16:31]
	v_mfma_f32_32x32x16_bf16 v[0:15], v[246:249], v[222:225], v[0:15]
	s_add_i32 s0, 0, 0x12000
	v_add3_u32 v165, 0, v167, v179
	v_add3_u32 v164, v182, v164, s0
	v_add3_u32 v172, 0, v180, v181
	ds_read_b128 v[168:171], v165
	ds_read_b128 v[182:185], v165 offset:4608
	ds_read_b128 v[186:189], v165 offset:9216
	ds_read_b128 v[190:193], v165 offset:13824
	ds_read_b64_tr_b16 v[218:219], v172 offset:36864
	ds_read_b64_tr_b16 v[220:221], v172 offset:39168
	ds_read_b64_tr_b16 v[222:223], v172 offset:36928
	ds_read_b64_tr_b16 v[224:225], v172 offset:39232
	s_waitcnt lgkmcnt(2)
	v_mfma_f32_32x32x16_bf16 v[112:127], v[218:221], v[168:171], v[112:127]
	v_add_u32_e32 v166, s0, v166
	s_waitcnt vmcnt(7)
	ds_write_b128 v166, v[152:155]
	s_waitcnt vmcnt(6)
	ds_write_b128 v164, v[156:159] offset:36864
	v_add_u32_e32 v217, 0x9000, v172
	s_add_i32 s3, s3, s15
	s_cmp_gt_i32 s3, 63
	s_waitcnt lgkmcnt(2)
	v_mfma_f32_32x32x16_bf16 v[96:111], v[222:225], v[168:171], v[96:111]
	v_mfma_f32_32x32x16_bf16 v[48:63], v[218:221], v[186:189], v[48:63]
	v_mfma_f32_32x32x16_bf16 v[32:47], v[222:225], v[186:189], v[32:47]
	v_mfma_f32_32x32x16_bf16 v[80:95], v[218:221], v[182:185], v[80:95]
	v_mfma_f32_32x32x16_bf16 v[64:79], v[222:225], v[182:185], v[64:79]
	v_mfma_f32_32x32x16_bf16 v[16:31], v[218:221], v[190:193], v[16:31]
	v_mfma_f32_32x32x16_bf16 v[0:15], v[222:225], v[190:193], v[0:15]
	ds_read_b128 v[152:155], v165 offset:32
	ds_read_b128 v[156:159], v165 offset:4640
	ds_read_b128 v[168:171], v165 offset:9248
	ds_read_b128 v[182:185], v165 offset:13856
	ds_read_b64_tr_b16 v[186:187], v172 offset:46080
	ds_read_b64_tr_b16 v[188:189], v172 offset:48384
	ds_read_b64_tr_b16 v[190:191], v172 offset:46144
	ds_read_b64_tr_b16 v[192:193], v172 offset:48448
	s_waitcnt vmcnt(5)
	ds_write_b128 v166, v[144:147] offset:9216
	s_waitcnt vmcnt(4)
	ds_write_b128 v164, v[148:151] offset:46080
	s_waitcnt lgkmcnt(4)
	v_mfma_f32_32x32x16_bf16 v[112:127], v[186:189], v[152:155], v[112:127]
	s_waitcnt lgkmcnt(2)
	v_mfma_f32_32x32x16_bf16 v[96:111], v[190:193], v[152:155], v[96:111]
	v_mfma_f32_32x32x16_bf16 v[48:63], v[186:189], v[168:171], v[48:63]
	v_mfma_f32_32x32x16_bf16 v[32:47], v[190:193], v[168:171], v[32:47]
	v_mfma_f32_32x32x16_bf16 v[80:95], v[186:189], v[156:159], v[80:95]
	v_mfma_f32_32x32x16_bf16 v[64:79], v[190:193], v[156:159], v[64:79]
	v_mfma_f32_32x32x16_bf16 v[16:31], v[186:189], v[182:185], v[16:31]
	v_mfma_f32_32x32x16_bf16 v[0:15], v[190:193], v[182:185], v[0:15]
	ds_read_b128 v[144:147], v165 offset:64
	ds_read_b128 v[148:151], v165 offset:4672
	ds_read_b128 v[152:155], v165 offset:9280
	ds_read_b128 v[156:159], v165 offset:13888
	ds_read_b64_tr_b16 v[168:169], v172 offset:55296
	ds_read_b64_tr_b16 v[170:171], v172 offset:57600
	ds_read_b64_tr_b16 v[182:183], v172 offset:55360
	ds_read_b64_tr_b16 v[184:185], v172 offset:57664
	s_waitcnt vmcnt(3)
	ds_write_b128 v166, v[136:139] offset:18432
	s_waitcnt vmcnt(2)
	ds_write_b128 v164, v[140:143] offset:55296
	s_waitcnt lgkmcnt(4)
	v_mfma_f32_32x32x16_bf16 v[112:127], v[168:171], v[144:147], v[112:127]
	s_waitcnt lgkmcnt(2)
	v_mfma_f32_32x32x16_bf16 v[96:111], v[182:185], v[144:147], v[96:111]
	v_mfma_f32_32x32x16_bf16 v[48:63], v[168:171], v[152:155], v[48:63]
	v_mfma_f32_32x32x16_bf16 v[32:47], v[182:185], v[152:155], v[32:47]
	v_mfma_f32_32x32x16_bf16 v[80:95], v[168:171], v[148:151], v[80:95]
	v_mfma_f32_32x32x16_bf16 v[64:79], v[182:185], v[148:151], v[64:79]
	v_mfma_f32_32x32x16_bf16 v[16:31], v[168:171], v[156:159], v[16:31]
	v_mfma_f32_32x32x16_bf16 v[0:15], v[182:185], v[156:159], v[0:15]
	ds_read_b128 v[136:139], v165 offset:96
	ds_read_b128 v[140:143], v165 offset:4704
	ds_read_b128 v[144:147], v165 offset:9312
	ds_read_b128 v[148:151], v165 offset:13920
	ds_read_b64_tr_b16 v[152:153], v172 offset:64512
	ds_read_b64_tr_b16 v[154:155], v217 offset:29952
	ds_read_b64_tr_b16 v[156:157], v172 offset:64576
	ds_read_b64_tr_b16 v[158:159], v217 offset:30016
	s_waitcnt vmcnt(1)
	ds_write_b128 v166, v[128:131] offset:27648
	s_waitcnt vmcnt(0)
	ds_write_b128 v164, v[132:135] offset:64512
	s_waitcnt lgkmcnt(0)
	s_barrier
; template <int BM, class Epi>
; DI void gemm_tile(const bf16_t* __restrict__ A, int lda, const bf16_t* __restrict__ B, int ldb, int K, int row0, int col0, const Epi& epi, char* smem) {
;     ...
;     for (int kt = 0; kt < nk; ++kt) {
;         const char* cur = smem + (kt & 1) * GSTAGE;
;         char* nxt = smem + ((kt & 1) ^ 1) * GSTAGE;
;         const bool w1 = kt + 1 < nk, l2 = kt + 2 < nk;
;         const bf16_t* a2 = ag + (size_t)(kt + 2) * 64; const bf16_t* b2 = bg + (size_t)(kt + 2) * 64 * ldb;
; #pragma unroll
;         for (int s = 0; s < 4; ++s) {
;             bf16x8 xf[MI], wf[2];
; #pragma unroll
;             for (int mi = 0; mi < MI; ++mi) xf[mi] = *(const bf16x8*)(cur + xoff + mi * 32 * GA_S + s * 32);
; #pragma unroll
;             for (int ni = 0; ni < 2; ++ni) {
;                 const char* wp = cur + woff + s * 16 * GB_S + ni * 64;
;                 wf[ni] = cat8(tr_read(wp), tr_read(wp + 4 * GB_S));
;             }
; #pragma unroll
;             for (int mi = 0; mi < MI; ++mi)
; #pragma unroll
;                 for (int ni = 0; ni < 2; ++ni) acc[mi][ni] = mfma32(wf[ni], xf[mi], acc[mi][ni]);
;             if (w1) {
;                 if (s < NA_) *(u32x4*)(nxt + aw + 64 * s * GA_S) = ra[s];
;                 *(u32x4*)(nxt + bw + 16 * s * GB_S) = rb[s];
;             }
;             if (l2) {
;                 if (s < NA_) ra[s] = *(const u32x4*)(a2 + (size_t)(64 * s) * lda);
;                 rb[s] = *(const u32x4*)(b2 + (size_t)(16 * s) * ldb);
;             }
;         }
;         __syncthreads();
;     }
; #pragma unroll
;     for (int mi = 0; mi < MI; ++mi) epi(acc[mi][0], acc[mi][1], row0 + wm * (BM / 2) + mi * 32 + l31, col0 + wn * 64, hh);
;     DI void operator()(const f32x16& a0, const f32x16& a1, int row, int cbase, int hh) const {
;         const int s = row < RL ? (row >> 13) : 4;
;         const float* gp = gate + s * 9216;
;         bf16_t* yp = Y + (size_t)row * 1024;
; #pragma unroll
;         for (int ni = 0; ni < 2; ++ni)
; #pragma unroll
;             for (int q4 = 0; q4 < 4; ++q4) {
;                 const int c = cbase + ni * 32 + 8 * q4 + 4 * hh;
;                 const f32x4 g = *(const f32x4*)(gp + c);
;                 const f32x16& v = ni ? a1 : a0;
;                 u32x2 w; w.x = pk2(coef * g[0] * v[4 * q4], coef * g[1] * v[4 * q4 + 1]); w.y = pk2(coef * g[2] * v[4 * q4 + 2], coef * g[3] * v[4 * q4 + 3]);
	v_mfma_f32_32x32x16_bf16 v[112:127], v[152:155], v[136:139], v[112:127]
	v_mfma_f32_32x32x16_bf16 v[96:111], v[156:159], v[136:139], v[96:111]
	v_mfma_f32_32x32x16_bf16 v[48:63], v[152:155], v[144:147], v[48:63]
	v_mfma_f32_32x32x16_bf16 v[32:47], v[156:159], v[144:147], v[32:47]
	v_mfma_f32_32x32x16_bf16 v[80:95], v[152:155], v[140:143], v[80:95]
	v_mfma_f32_32x32x16_bf16 v[64:79], v[156:159], v[140:143], v[64:79]
	v_mfma_f32_32x32x16_bf16 v[16:31], v[152:155], v[148:151], v[16:31]
	v_mfma_f32_32x32x16_bf16 v[0:15], v[156:159], v[148:151], v[0:15]
	v_add3_u32 v156, s0, v167, v179
	v_add3_u32 v157, s0, v180, v181
	ds_read_b128 v[128:131], v156 offset:4608
	ds_read_b128 v[132:135], v156 offset:9216
	ds_read_b128 v[136:139], v156 offset:13824
	ds_read_b64_tr_b16 v[140:141], v157 offset:36864
	ds_read_b64_tr_b16 v[142:143], v157 offset:39168
	ds_read_b64_tr_b16 v[144:145], v157 offset:36928
	ds_read_b64_tr_b16 v[146:147], v157 offset:39232
	ds_read_b128 v[148:151], v156
	ds_read_b128 v[152:155], v156 offset:32
	v_add_u32_e32 v158, 0x9000, v157
	v_readlane_b32 s0, v253, 5
	v_readlane_b32 s1, v253, 6
	s_waitcnt lgkmcnt(1)
	v_mfma_f32_32x32x16_bf16 v[112:127], v[140:143], v[148:151], v[112:127]
	v_mfma_f32_32x32x16_bf16 v[96:111], v[144:147], v[148:151], v[96:111]
	v_mfma_f32_32x32x16_bf16 v[48:63], v[140:143], v[132:135], v[48:63]
	v_mfma_f32_32x32x16_bf16 v[32:47], v[144:147], v[132:135], v[32:47]
	v_mfma_f32_32x32x16_bf16 v[80:95], v[140:143], v[128:131], v[80:95]
	v_mfma_f32_32x32x16_bf16 v[64:79], v[144:147], v[128:131], v[64:79]
	v_mfma_f32_32x32x16_bf16 v[16:31], v[140:143], v[136:139], v[16:31]
	v_mfma_f32_32x32x16_bf16 v[0:15], v[144:147], v[136:139], v[0:15]
	ds_read_b128 v[128:131], v156 offset:4640
	ds_read_b128 v[132:135], v156 offset:9248
	ds_read_b128 v[136:139], v156 offset:13856
	ds_read_b64_tr_b16 v[140:141], v157 offset:46080
	ds_read_b64_tr_b16 v[142:143], v157 offset:48384
	ds_read_b64_tr_b16 v[144:145], v157 offset:46144
	ds_read_b64_tr_b16 v[146:147], v157 offset:48448
	s_waitcnt lgkmcnt(2)
	v_mfma_f32_32x32x16_bf16 v[112:127], v[140:143], v[152:155], v[112:127]
	s_waitcnt lgkmcnt(0)
	v_mfma_f32_32x32x16_bf16 v[96:111], v[144:147], v[152:155], v[96:111]
	v_mfma_f32_32x32x16_bf16 v[48:63], v[140:143], v[132:135], v[48:63]
	v_mfma_f32_32x32x16_bf16 v[32:47], v[144:147], v[132:135], v[32:47]
	v_mfma_f32_32x32x16_bf16 v[80:95], v[140:143], v[128:131], v[80:95]
	v_mfma_f32_32x32x16_bf16 v[64:79], v[144:147], v[128:131], v[64:79]
	v_mfma_f32_32x32x16_bf16 v[16:31], v[140:143], v[136:139], v[16:31]
	v_mfma_f32_32x32x16_bf16 v[0:15], v[144:147], v[136:139], v[0:15]
	ds_read_b128 v[128:131], v156 offset:64
	ds_read_b128 v[132:135], v156 offset:4672
	ds_read_b128 v[136:139], v156 offset:9280
	ds_read_b128 v[140:143], v156 offset:13888
	ds_read_b64_tr_b16 v[144:145], v157 offset:55296
	ds_read_b64_tr_b16 v[146:147], v157 offset:57600
	ds_read_b64_tr_b16 v[148:149], v157 offset:55360
	ds_read_b64_tr_b16 v[150:151], v157 offset:57664
	s_waitcnt lgkmcnt(2)
	v_mfma_f32_32x32x16_bf16 v[112:127], v[144:147], v[128:131], v[112:127]
	s_waitcnt lgkmcnt(0)
	v_mfma_f32_32x32x16_bf16 v[96:111], v[148:151], v[128:131], v[96:111]
	v_mfma_f32_32x32x16_bf16 v[48:63], v[144:147], v[136:139], v[48:63]
	v_mfma_f32_32x32x16_bf16 v[32:47], v[148:151], v[136:139], v[32:47]
	v_mfma_f32_32x32x16_bf16 v[80:95], v[144:147], v[132:135], v[80:95]
	v_mfma_f32_32x32x16_bf16 v[64:79], v[148:151], v[132:135], v[64:79]
	v_mfma_f32_32x32x16_bf16 v[16:31], v[144:147], v[140:143], v[16:31]
	v_mfma_f32_32x32x16_bf16 v[0:15], v[148:151], v[140:143], v[0:15]
	ds_read_b128 v[128:131], v156 offset:96
	ds_read_b128 v[132:135], v156 offset:4704
	ds_read_b128 v[136:139], v156 offset:9312
	ds_read_b128 v[140:143], v156 offset:13920
	ds_read_b64_tr_b16 v[144:145], v157 offset:64512
	ds_read_b64_tr_b16 v[146:147], v158 offset:29952
	ds_read_b64_tr_b16 v[148:149], v157 offset:64576
	ds_read_b64_tr_b16 v[150:151], v158 offset:30016
	s_waitcnt lgkmcnt(0)
	s_barrier
	v_mfma_f32_32x32x16_bf16 v[112:127], v[144:147], v[128:131], v[112:127]
	v_mfma_f32_32x32x16_bf16 v[96:111], v[148:151], v[128:131], v[96:111]
	v_or_b32_e32 v128, s16, v176
	v_and_b32_e32 v129, 0xc0, v175
	v_add_u32_e32 v128, v128, v178
	v_lshlrev_b32_e32 v130, 2, v177
	v_mfma_f32_32x32x16_bf16 v[48:63], v[144:147], v[136:139], v[48:63]
	v_mfma_f32_32x32x16_bf16 v[32:47], v[148:151], v[136:139], v[32:47]
	v_or3_b32 v138, v130, v129, s10
	v_min_i32_e32 v129, 0x8000, v128
	v_ashrrev_i32_e32 v129, 13, v129
	v_mul_i32_i24_e32 v130, 0x2400, v129
	v_ashrrev_i32_e32 v131, 31, v130
	v_ashrrev_i32_e32 v129, 31, v128
	v_ashrrev_i32_e32 v139, 31, v138
	v_mfma_f32_32x32x16_bf16 v[80:95], v[144:147], v[132:135], v[80:95]
	v_mfma_f32_32x32x16_bf16 v[64:79], v[148:151], v[132:135], v[64:79]
	v_lshl_add_u64 v[132:133], v[130:131], 2, s[4:5]
	v_lshlrev_b64 v[130:131], 11, v[128:129]
	v_mfma_f32_32x32x16_bf16 v[16:31], v[144:147], v[140:143], v[16:31]
	v_mfma_f32_32x32x16_bf16 v[0:15], v[148:151], v[140:143], v[0:15]
	v_lshl_add_u64 v[140:141], s[0:1], 0, v[130:131]
	v_lshlrev_b64 v[130:131], 2, v[138:139]
	v_lshl_add_u64 v[132:133], v[132:133], 0, v[130:131]
	global_load_dwordx4 v[134:137], v[132:133], off
	s_waitcnt vmcnt(0)
	v_pk_mul_f32 v[134:135], v[134:135], 0.5 op_sel_hi:[1,0]
	s_nop 0
	v_pk_mul_f32 v[112:113], v[112:113], v[134:135]
	s_nop 0
	v_cvt_pk_bf16_f32 v134, v112, v113
	v_pk_mul_f32 v[112:113], v[136:137], 0.5 op_sel_hi:[1,0]
	s_nop 0
	v_pk_mul_f32 v[112:113], v[114:115], v[112:113]
	s_nop 0
	v_cvt_pk_bf16_f32 v135, v112, v113
	v_lshlrev_b64 v[112:113], 1, v[138:139]
	v_lshl_add_u64 v[138:139], v[140:141], 0, v[112:113]
	global_store_dwordx2 v[138:139], v[134:135], off
	global_load_dwordx4 v[134:137], v[132:133], off offset:32
	s_waitcnt vmcnt(0)
; DI unsigned pk2(float a, float b) { f32x2 v = {a, b}; bfx2 r = __builtin_convertvector(v, bfx2); return __builtin_bit_cast(unsigned, r); }
;     DI void operator()(const f32x16& a0, const f32x16& a1, int row, int cbase, int hh) const {
;         const int s = row < RL ? (row >> 13) : 4;
;         const float* gp = gate + s * 9216;
;         bf16_t* yp = Y + (size_t)row * 1024;
; #pragma unroll
;         for (int ni = 0; ni < 2; ++ni)
; #pragma unroll
;             for (int q4 = 0; q4 < 4; ++q4) {
;                 const int c = cbase + ni * 32 + 8 * q4 + 4 * hh;
;                 const f32x4 g = *(const f32x4*)(gp + c);
;                 const f32x16& v = ni ? a1 : a0;
;                 u32x2 w; w.x = pk2(coef * g[0] * v[4 * q4], coef * g[1] * v[4 * q4 + 1]); w.y = pk2(coef * g[2] * v[4 * q4 + 2], coef * g[3] * v[4 * q4 + 3]);
;                 *(u32x2*)(yp + c) = w;
;             }
	v_pk_mul_f32 v[114:115], v[134:135], 0.5 op_sel_hi:[1,0]
	s_nop 0
	v_pk_mul_f32 v[114:115], v[116:117], v[114:115]
	v_pk_mul_f32 v[116:117], v[136:137], 0.5 op_sel_hi:[1,0]
	v_cvt_pk_bf16_f32 v114, v114, v115
	v_pk_mul_f32 v[116:117], v[118:119], v[116:117]
	s_nop 0
	v_cvt_pk_bf16_f32 v115, v116, v117
	global_store_dwordx2 v[138:139], v[114:115], off offset:16
	global_load_dwordx4 v[114:117], v[132:133], off offset:64
	s_waitcnt vmcnt(0)
	v_pk_mul_f32 v[114:115], v[114:115], 0.5 op_sel_hi:[1,0]
	v_pk_mul_f32 v[116:117], v[116:117], 0.5 op_sel_hi:[1,0]
	v_pk_mul_f32 v[114:115], v[120:121], v[114:115]
	v_pk_mul_f32 v[116:117], v[122:123], v[116:117]
	v_cvt_pk_bf16_f32 v114, v114, v115
	v_cvt_pk_bf16_f32 v115, v116, v117
	global_store_dwordx2 v[138:139], v[114:115], off offset:32
	global_load_dwordx4 v[114:117], v[132:133], off offset:96
	s_waitcnt vmcnt(0)
	v_pk_mul_f32 v[114:115], v[114:115], 0.5 op_sel_hi:[1,0]
	v_pk_mul_f32 v[116:117], v[116:117], 0.5 op_sel_hi:[1,0]
	v_pk_mul_f32 v[114:115], v[124:125], v[114:115]
	v_pk_mul_f32 v[116:117], v[126:127], v[116:117]
	v_cvt_pk_bf16_f32 v114, v114, v115
	v_cvt_pk_bf16_f32 v115, v116, v117
	global_store_dwordx2 v[138:139], v[114:115], off offset:48
	global_load_dwordx4 v[114:117], v[132:133], off offset:128
	s_waitcnt vmcnt(0)
	v_pk_mul_f32 v[114:115], v[114:115], 0.5 op_sel_hi:[1,0]
	s_nop 0
	v_pk_mul_f32 v[96:97], v[96:97], v[114:115]
	v_pk_mul_f32 v[114:115], v[116:117], 0.5 op_sel_hi:[1,0]
	v_cvt_pk_bf16_f32 v96, v96, v97
	v_pk_mul_f32 v[98:99], v[98:99], v[114:115]
	s_nop 0
	v_cvt_pk_bf16_f32 v97, v98, v99
	global_store_dwordx2 v[138:139], v[96:97], off offset:64
	global_load_dwordx4 v[96:99], v[132:133], off offset:160
	s_waitcnt vmcnt(0)
	v_pk_mul_f32 v[96:97], v[96:97], 0.5 op_sel_hi:[1,0]
	v_pk_mul_f32 v[98:99], v[98:99], 0.5 op_sel_hi:[1,0]
	v_pk_mul_f32 v[96:97], v[100:101], v[96:97]
	v_pk_mul_f32 v[98:99], v[102:103], v[98:99]
	v_cvt_pk_bf16_f32 v96, v96, v97
	v_cvt_pk_bf16_f32 v97, v98, v99
	global_store_dwordx2 v[138:139], v[96:97], off offset:80
	global_load_dwordx4 v[96:99], v[132:133], off offset:192
	s_waitcnt vmcnt(0)
	v_pk_mul_f32 v[96:97], v[96:97], 0.5 op_sel_hi:[1,0]
	v_pk_mul_f32 v[98:99], v[98:99], 0.5 op_sel_hi:[1,0]
	v_pk_mul_f32 v[96:97], v[104:105], v[96:97]
	v_pk_mul_f32 v[98:99], v[106:107], v[98:99]
	v_cvt_pk_bf16_f32 v96, v96, v97
	v_cvt_pk_bf16_f32 v97, v98, v99
	global_store_dwordx2 v[138:139], v[96:97], off offset:96
	global_load_dwordx4 v[96:99], v[132:133], off offset:224
	s_waitcnt vmcnt(0)
	v_pk_mul_f32 v[96:97], v[96:97], 0.5 op_sel_hi:[1,0]
	v_pk_mul_f32 v[98:99], v[98:99], 0.5 op_sel_hi:[1,0]
	v_pk_mul_f32 v[96:97], v[108:109], v[96:97]
	v_pk_mul_f32 v[98:99], v[110:111], v[98:99]
	v_cvt_pk_bf16_f32 v96, v96, v97
	v_cvt_pk_bf16_f32 v97, v98, v99
	global_store_dwordx2 v[138:139], v[96:97], off offset:112
	v_or_b32_e32 v96, 32, v128
	v_min_i32_e32 v97, 0x8000, v96
	v_ashrrev_i32_e32 v97, 13, v97
	v_mul_i32_i24_e32 v98, 0x2400, v97
	v_ashrrev_i32_e32 v99, 31, v98
	v_ashrrev_i32_e32 v97, 31, v96
	v_lshl_add_u64 v[98:99], v[98:99], 2, s[4:5]
	v_lshlrev_b64 v[96:97], 11, v[96:97]
	v_lshl_add_u64 v[102:103], s[0:1], 0, v[96:97]
	v_lshl_add_u64 v[96:97], v[98:99], 0, v[130:131]
	global_load_dwordx4 v[98:101], v[96:97], off
	s_waitcnt vmcnt(0)
	v_pk_mul_f32 v[98:99], v[98:99], 0.5 op_sel_hi:[1,0]
	s_nop 0
	v_pk_mul_f32 v[80:81], v[80:81], v[98:99]
	v_pk_mul_f32 v[98:99], v[100:101], 0.5 op_sel_hi:[1,0]
	v_cvt_pk_bf16_f32 v80, v80, v81
	v_pk_mul_f32 v[82:83], v[82:83], v[98:99]
	v_lshl_add_u64 v[98:99], v[102:103], 0, v[112:113]
	v_cvt_pk_bf16_f32 v81, v82, v83
	global_store_dwordx2 v[98:99], v[80:81], off
	global_load_dwordx4 v[80:83], v[96:97], off offset:32
	s_waitcnt vmcnt(0)
	v_pk_mul_f32 v[80:81], v[80:81], 0.5 op_sel_hi:[1,0]
	v_pk_mul_f32 v[82:83], v[82:83], 0.5 op_sel_hi:[1,0]
	v_pk_mul_f32 v[80:81], v[84:85], v[80:81]
	v_pk_mul_f32 v[82:83], v[86:87], v[82:83]
	v_cvt_pk_bf16_f32 v80, v80, v81
	v_cvt_pk_bf16_f32 v81, v82, v83
	global_store_dwordx2 v[98:99], v[80:81], off offset:16
	global_load_dwordx4 v[80:83], v[96:97], off offset:64
	s_waitcnt vmcnt(0)
	v_pk_mul_f32 v[80:81], v[80:81], 0.5 op_sel_hi:[1,0]
	v_pk_mul_f32 v[82:83], v[82:83], 0.5 op_sel_hi:[1,0]
	v_pk_mul_f32 v[80:81], v[88:89], v[80:81]
	v_pk_mul_f32 v[82:83], v[90:91], v[82:83]
	v_cvt_pk_bf16_f32 v80, v80, v81
	v_cvt_pk_bf16_f32 v81, v82, v83
	global_store_dwordx2 v[98:99], v[80:81], off offset:32
	global_load_dwordx4 v[80:83], v[96:97], off offset:96
	s_waitcnt vmcnt(0)
	v_pk_mul_f32 v[80:81], v[80:81], 0.5 op_sel_hi:[1,0]
	v_pk_mul_f32 v[82:83], v[82:83], 0.5 op_sel_hi:[1,0]
	v_pk_mul_f32 v[80:81], v[92:93], v[80:81]
	v_pk_mul_f32 v[82:83], v[94:95], v[82:83]
	v_cvt_pk_bf16_f32 v80, v80, v81
	v_cvt_pk_bf16_f32 v81, v82, v83
	global_store_dwordx2 v[98:99], v[80:81], off offset:48
	global_load_dwordx4 v[80:83], v[96:97], off offset:128
	s_waitcnt vmcnt(0)
	v_pk_mul_f32 v[80:81], v[80:81], 0.5 op_sel_hi:[1,0]
	s_nop 0
	v_pk_mul_f32 v[64:65], v[64:65], v[80:81]
	v_pk_mul_f32 v[80:81], v[82:83], 0.5 op_sel_hi:[1,0]
	v_cvt_pk_bf16_f32 v64, v64, v65
	v_pk_mul_f32 v[66:67], v[66:67], v[80:81]
	s_nop 0
	v_cvt_pk_bf16_f32 v65, v66, v67
	global_store_dwordx2 v[98:99], v[64:65], off offset:64
	global_load_dwordx4 v[64:67], v[96:97], off offset:160
	s_waitcnt vmcnt(0)
	v_pk_mul_f32 v[64:65], v[64:65], 0.5 op_sel_hi:[1,0]
	v_pk_mul_f32 v[66:67], v[66:67], 0.5 op_sel_hi:[1,0]
	v_pk_mul_f32 v[64:65], v[68:69], v[64:65]
	v_pk_mul_f32 v[66:67], v[70:71], v[66:67]
	v_cvt_pk_bf16_f32 v64, v64, v65
	v_cvt_pk_bf16_f32 v65, v66, v67
	global_store_dwordx2 v[98:99], v[64:65], off offset:80
	global_load_dwordx4 v[64:67], v[96:97], off offset:192
	s_waitcnt vmcnt(0)
; DI unsigned pk2(float a, float b) { f32x2 v = {a, b}; bfx2 r = __builtin_convertvector(v, bfx2); return __builtin_bit_cast(unsigned, r); }
;     DI void operator()(const f32x16& a0, const f32x16& a1, int row, int cbase, int hh) const {
;         const int s = row < RL ? (row >> 13) : 4;
;         const float* gp = gate + s * 9216;
;         bf16_t* yp = Y + (size_t)row * 1024;
; #pragma unroll
;         for (int ni = 0; ni < 2; ++ni)
; #pragma unroll
;             for (int q4 = 0; q4 < 4; ++q4) {
;                 const int c = cbase + ni * 32 + 8 * q4 + 4 * hh;
;                 const f32x4 g = *(const f32x4*)(gp + c);
;                 const f32x16& v = ni ? a1 : a0;
;                 u32x2 w; w.x = pk2(coef * g[0] * v[4 * q4], coef * g[1] * v[4 * q4 + 1]); w.y = pk2(coef * g[2] * v[4 * q4 + 2], coef * g[3] * v[4 * q4 + 3]);
;                 *(u32x2*)(yp + c) = w;
;             }
	v_pk_mul_f32 v[64:65], v[64:65], 0.5 op_sel_hi:[1,0]
	v_pk_mul_f32 v[66:67], v[66:67], 0.5 op_sel_hi:[1,0]
	v_pk_mul_f32 v[64:65], v[72:73], v[64:65]
	v_pk_mul_f32 v[66:67], v[74:75], v[66:67]
	v_cvt_pk_bf16_f32 v64, v64, v65
	v_cvt_pk_bf16_f32 v65, v66, v67
	global_store_dwordx2 v[98:99], v[64:65], off offset:96
	global_load_dwordx4 v[64:67], v[96:97], off offset:224
	s_waitcnt vmcnt(0)
	v_pk_mul_f32 v[64:65], v[64:65], 0.5 op_sel_hi:[1,0]
	v_pk_mul_f32 v[66:67], v[66:67], 0.5 op_sel_hi:[1,0]
	v_pk_mul_f32 v[64:65], v[76:77], v[64:65]
	v_pk_mul_f32 v[66:67], v[78:79], v[66:67]
	v_cvt_pk_bf16_f32 v64, v64, v65
	v_cvt_pk_bf16_f32 v65, v66, v67
	global_store_dwordx2 v[98:99], v[64:65], off offset:112
	v_or_b32_e32 v64, 64, v128
	v_min_i32_e32 v65, 0x8000, v64
	v_ashrrev_i32_e32 v65, 13, v65
	v_mul_i32_i24_e32 v66, 0x2400, v65
	v_ashrrev_i32_e32 v67, 31, v66
	v_ashrrev_i32_e32 v65, 31, v64
	v_lshl_add_u64 v[66:67], v[66:67], 2, s[4:5]
	v_lshlrev_b64 v[64:65], 11, v[64:65]
	v_lshl_add_u64 v[70:71], s[0:1], 0, v[64:65]
	v_lshl_add_u64 v[64:65], v[66:67], 0, v[130:131]
	global_load_dwordx4 v[66:69], v[64:65], off
	s_waitcnt vmcnt(0)
	v_pk_mul_f32 v[66:67], v[66:67], 0.5 op_sel_hi:[1,0]
	s_nop 0
	v_pk_mul_f32 v[48:49], v[48:49], v[66:67]
	v_pk_mul_f32 v[66:67], v[68:69], 0.5 op_sel_hi:[1,0]
	v_cvt_pk_bf16_f32 v48, v48, v49
	v_pk_mul_f32 v[50:51], v[50:51], v[66:67]
	v_lshl_add_u64 v[66:67], v[70:71], 0, v[112:113]
	v_cvt_pk_bf16_f32 v49, v50, v51
	global_store_dwordx2 v[66:67], v[48:49], off
	global_load_dwordx4 v[48:51], v[64:65], off offset:32
	s_waitcnt vmcnt(0)
	v_pk_mul_f32 v[48:49], v[48:49], 0.5 op_sel_hi:[1,0]
	v_pk_mul_f32 v[50:51], v[50:51], 0.5 op_sel_hi:[1,0]
	v_pk_mul_f32 v[48:49], v[52:53], v[48:49]
	v_pk_mul_f32 v[50:51], v[54:55], v[50:51]
	v_cvt_pk_bf16_f32 v48, v48, v49
	v_cvt_pk_bf16_f32 v49, v50, v51
	global_store_dwordx2 v[66:67], v[48:49], off offset:16
	global_load_dwordx4 v[48:51], v[64:65], off offset:64
	s_waitcnt vmcnt(0)
	v_pk_mul_f32 v[48:49], v[48:49], 0.5 op_sel_hi:[1,0]
	v_pk_mul_f32 v[50:51], v[50:51], 0.5 op_sel_hi:[1,0]
	v_pk_mul_f32 v[48:49], v[56:57], v[48:49]
	v_pk_mul_f32 v[50:51], v[58:59], v[50:51]
	v_cvt_pk_bf16_f32 v48, v48, v49
	v_cvt_pk_bf16_f32 v49, v50, v51
	global_store_dwordx2 v[66:67], v[48:49], off offset:32
	global_load_dwordx4 v[48:51], v[64:65], off offset:96
	s_waitcnt vmcnt(0)
	v_pk_mul_f32 v[48:49], v[48:49], 0.5 op_sel_hi:[1,0]
	v_pk_mul_f32 v[50:51], v[50:51], 0.5 op_sel_hi:[1,0]
	v_pk_mul_f32 v[48:49], v[60:61], v[48:49]
	v_pk_mul_f32 v[50:51], v[62:63], v[50:51]
	v_cvt_pk_bf16_f32 v48, v48, v49
	v_cvt_pk_bf16_f32 v49, v50, v51
	global_store_dwordx2 v[66:67], v[48:49], off offset:48
	global_load_dwordx4 v[48:51], v[64:65], off offset:128
	s_waitcnt vmcnt(0)
	v_pk_mul_f32 v[48:49], v[48:49], 0.5 op_sel_hi:[1,0]
	s_nop 0
	v_pk_mul_f32 v[32:33], v[32:33], v[48:49]
	v_pk_mul_f32 v[48:49], v[50:51], 0.5 op_sel_hi:[1,0]
	v_cvt_pk_bf16_f32 v32, v32, v33
	v_pk_mul_f32 v[34:35], v[34:35], v[48:49]
	s_nop 0
	v_cvt_pk_bf16_f32 v33, v34, v35
	global_store_dwordx2 v[66:67], v[32:33], off offset:64
	global_load_dwordx4 v[32:35], v[64:65], off offset:160
	s_waitcnt vmcnt(0)
	v_pk_mul_f32 v[32:33], v[32:33], 0.5 op_sel_hi:[1,0]
	v_pk_mul_f32 v[34:35], v[34:35], 0.5 op_sel_hi:[1,0]
	v_pk_mul_f32 v[32:33], v[36:37], v[32:33]
	v_pk_mul_f32 v[34:35], v[38:39], v[34:35]
	v_cvt_pk_bf16_f32 v32, v32, v33
	v_cvt_pk_bf16_f32 v33, v34, v35
	global_store_dwordx2 v[66:67], v[32:33], off offset:80
	global_load_dwordx4 v[32:35], v[64:65], off offset:192
	s_waitcnt vmcnt(0)
	v_pk_mul_f32 v[32:33], v[32:33], 0.5 op_sel_hi:[1,0]
	v_pk_mul_f32 v[34:35], v[34:35], 0.5 op_sel_hi:[1,0]
	v_pk_mul_f32 v[32:33], v[40:41], v[32:33]
	v_pk_mul_f32 v[34:35], v[42:43], v[34:35]
	v_cvt_pk_bf16_f32 v32, v32, v33
	v_cvt_pk_bf16_f32 v33, v34, v35
	global_store_dwordx2 v[66:67], v[32:33], off offset:96
	global_load_dwordx4 v[32:35], v[64:65], off offset:224
	s_waitcnt vmcnt(0)
; DI unsigned pk2(float a, float b) { f32x2 v = {a, b}; bfx2 r = __builtin_convertvector(v, bfx2); return __builtin_bit_cast(unsigned, r); }
;     DI void operator()(const f32x16& a0, const f32x16& a1, int row, int cbase, int hh) const {
;         const int s = row < RL ? (row >> 13) : 4;
;         const float* gp = gate + s * 9216;
;         bf16_t* yp = Y + (size_t)row * 1024;
; #pragma unroll
;         for (int ni = 0; ni < 2; ++ni)
; #pragma unroll
;             for (int q4 = 0; q4 < 4; ++q4) {
;                 const int c = cbase + ni * 32 + 8 * q4 + 4 * hh;
;                 const f32x4 g = *(const f32x4*)(gp + c);
;                 const f32x16& v = ni ? a1 : a0;
;                 u32x2 w; w.x = pk2(coef * g[0] * v[4 * q4], coef * g[1] * v[4 * q4 + 1]); w.y = pk2(coef * g[2] * v[4 * q4 + 2], coef * g[3] * v[4 * q4 + 3]);
;                 *(u32x2*)(yp + c) = w;
;             }
	v_pk_mul_f32 v[32:33], v[32:33], 0.5 op_sel_hi:[1,0]
	v_pk_mul_f32 v[34:35], v[34:35], 0.5 op_sel_hi:[1,0]
	v_pk_mul_f32 v[32:33], v[44:45], v[32:33]
	v_pk_mul_f32 v[34:35], v[46:47], v[34:35]
	v_cvt_pk_bf16_f32 v32, v32, v33
	v_cvt_pk_bf16_f32 v33, v34, v35
	global_store_dwordx2 v[66:67], v[32:33], off offset:112
	v_or_b32_e32 v32, 0x60, v128
	v_min_i32_e32 v33, 0x8000, v32
	v_ashrrev_i32_e32 v33, 13, v33
	v_mul_i32_i24_e32 v34, 0x2400, v33
	v_ashrrev_i32_e32 v35, 31, v34
	v_ashrrev_i32_e32 v33, 31, v32
	v_lshl_add_u64 v[34:35], v[34:35], 2, s[4:5]
	v_lshlrev_b64 v[32:33], 11, v[32:33]
	v_lshl_add_u64 v[38:39], s[0:1], 0, v[32:33]
	v_lshl_add_u64 v[32:33], v[34:35], 0, v[130:131]
	global_load_dwordx4 v[34:37], v[32:33], off
	s_waitcnt vmcnt(0)
	v_pk_mul_f32 v[34:35], v[34:35], 0.5 op_sel_hi:[1,0]
	s_nop 0
	v_pk_mul_f32 v[16:17], v[16:17], v[34:35]
	v_pk_mul_f32 v[34:35], v[36:37], 0.5 op_sel_hi:[1,0]
	v_cvt_pk_bf16_f32 v16, v16, v17
	v_pk_mul_f32 v[18:19], v[18:19], v[34:35]
	v_lshl_add_u64 v[34:35], v[38:39], 0, v[112:113]
	v_cvt_pk_bf16_f32 v17, v18, v19
	global_store_dwordx2 v[34:35], v[16:17], off
	global_load_dwordx4 v[16:19], v[32:33], off offset:32
	s_waitcnt vmcnt(0)
	v_pk_mul_f32 v[16:17], v[16:17], 0.5 op_sel_hi:[1,0]
	v_pk_mul_f32 v[18:19], v[18:19], 0.5 op_sel_hi:[1,0]
	v_pk_mul_f32 v[16:17], v[20:21], v[16:17]
	v_pk_mul_f32 v[18:19], v[22:23], v[18:19]
	v_cvt_pk_bf16_f32 v16, v16, v17
	v_cvt_pk_bf16_f32 v17, v18, v19
	global_store_dwordx2 v[34:35], v[16:17], off offset:16
	global_load_dwordx4 v[16:19], v[32:33], off offset:64
	s_waitcnt vmcnt(0)
	v_pk_mul_f32 v[16:17], v[16:17], 0.5 op_sel_hi:[1,0]
	v_pk_mul_f32 v[18:19], v[18:19], 0.5 op_sel_hi:[1,0]
	v_pk_mul_f32 v[16:17], v[24:25], v[16:17]
	v_pk_mul_f32 v[18:19], v[26:27], v[18:19]
	v_cvt_pk_bf16_f32 v16, v16, v17
	v_cvt_pk_bf16_f32 v17, v18, v19
	global_store_dwordx2 v[34:35], v[16:17], off offset:32
	global_load_dwordx4 v[16:19], v[32:33], off offset:96
	s_waitcnt vmcnt(0)
	v_pk_mul_f32 v[16:17], v[16:17], 0.5 op_sel_hi:[1,0]
	v_pk_mul_f32 v[18:19], v[18:19], 0.5 op_sel_hi:[1,0]
	v_pk_mul_f32 v[16:17], v[28:29], v[16:17]
	v_pk_mul_f32 v[18:19], v[30:31], v[18:19]
	v_cvt_pk_bf16_f32 v16, v16, v17
	v_cvt_pk_bf16_f32 v17, v18, v19
	global_store_dwordx2 v[34:35], v[16:17], off offset:48
	global_load_dwordx4 v[16:19], v[32:33], off offset:128
	s_waitcnt vmcnt(0)
	v_pk_mul_f32 v[16:17], v[16:17], 0.5 op_sel_hi:[1,0]
	s_nop 0
	v_pk_mul_f32 v[0:1], v[0:1], v[16:17]
	v_pk_mul_f32 v[16:17], v[18:19], 0.5 op_sel_hi:[1,0]
	v_cvt_pk_bf16_f32 v0, v0, v1
	v_pk_mul_f32 v[2:3], v[2:3], v[16:17]
	s_nop 0
	v_cvt_pk_bf16_f32 v1, v2, v3
	global_store_dwordx2 v[34:35], v[0:1], off offset:64
	global_load_dwordx4 v[0:3], v[32:33], off offset:160
	s_waitcnt vmcnt(0)
	v_pk_mul_f32 v[0:1], v[0:1], 0.5 op_sel_hi:[1,0]
	v_pk_mul_f32 v[2:3], v[2:3], 0.5 op_sel_hi:[1,0]
	v_pk_mul_f32 v[0:1], v[4:5], v[0:1]
	v_pk_mul_f32 v[2:3], v[6:7], v[2:3]
	v_cvt_pk_bf16_f32 v0, v0, v1
	v_cvt_pk_bf16_f32 v1, v2, v3
	global_store_dwordx2 v[34:35], v[0:1], off offset:80
	global_load_dwordx4 v[0:3], v[32:33], off offset:192
	s_waitcnt vmcnt(0)
	v_pk_mul_f32 v[0:1], v[0:1], 0.5 op_sel_hi:[1,0]
	v_pk_mul_f32 v[2:3], v[2:3], 0.5 op_sel_hi:[1,0]
	v_pk_mul_f32 v[0:1], v[8:9], v[0:1]
	v_pk_mul_f32 v[2:3], v[10:11], v[2:3]
	v_cvt_pk_bf16_f32 v0, v0, v1
	v_cvt_pk_bf16_f32 v1, v2, v3
	global_store_dwordx2 v[34:35], v[0:1], off offset:96
	global_load_dwordx4 v[0:3], v[32:33], off offset:224
	s_waitcnt vmcnt(0)
	v_pk_mul_f32 v[0:1], v[0:1], 0.5 op_sel_hi:[1,0]
	v_pk_mul_f32 v[2:3], v[2:3], 0.5 op_sel_hi:[1,0]
	v_pk_mul_f32 v[0:1], v[12:13], v[0:1]
	v_pk_mul_f32 v[2:3], v[14:15], v[2:3]
	v_cvt_pk_bf16_f32 v0, v0, v1
	v_cvt_pk_bf16_f32 v1, v2, v3
	global_store_dwordx2 v[34:35], v[0:1], off offset:112
	s_cbranch_scc0 .LBB0_1482
